# last layer: context DFT items of the prep phase (outputs unused there) not executed; latent DFT items dealt one per block
# speedup vs baseline: 1.0239x; 1.0088x over previous
; __device__ __forceinline__ int opaque_tid() { int t = threadIdx.x; asm volatile("" : "+v"(t)); return t; }
; __device__ __forceinline__ void phase_prep(const Params& P, int l, unsigned char* lds) {
;     ...
;     for (int item = blockIdx.x; item < ROWS / 64 + NBATCH * 20; item += G) {
;         const int tid = opaque_tid();
;         const int type = item >= ROWS / 64;
;         int r0, b, t0;
;         if (!type) { r0 = item * 64; b = r0 / TT; t0 = r0 - b * TT; }
;         else { const int idx = item - ROWS / 64; b = idx / 20; const int jb = idx - b * 20; t0 = (jb < 4) ? 64 * jb : CTX + 64 * (jb - 4); r0 = b * TT + t0; }
;         const bool is_ctx = t0 < CTX;
.LBB0_228:
	s_mov_b32 s101, s28
	v_readlane_b32 s100, v255, 0
	s_nop 3
	s_cmp_lg_u32 s100, 3
	s_cbranch_scc1 .Lprep_map_done
	s_cmp_lg_u32 s60, 0x100
	s_cbranch_scc1 .Lprep_map_done
	s_and_b32 s100, s28, 0xff
	s_lshr_b32 s101, s28, 8
	s_cmp_eq_u32 s101, 0
	s_cbranch_scc1 .Lprep_k0
	s_cmp_eq_u32 s101, 3
	s_cbranch_scc1 .Lprep_k3
	s_sub_u32 s101, s101, 1
	s_lshl_b32 s101, s101, 8
	s_add_u32 s101, s101, s100
	s_branch .Lprep_map_done
.Lprep_k3:
	s_cmp_lt_u32 s100, 0x40
	s_cbranch_scc0 .LBB0_227
	s_add_u32 s101, s100, 0x200
	s_branch .Lprep_map_done
.Lprep_k0:
	s_lshr_b32 s101, s100, 4
	s_mul_i32 s101, s101, 20
	s_and_b32 s100, s100, 15
	s_add_u32 s101, s101, s100
	s_add_u32 s101, s101, 0x244
.Lprep_map_done:
	s_cmpk_gt_i32 s101, 0x23f
	s_cselect_b64 s[38:39], -1, 0
	v_mov_b32_e32 v44, v200
	s_mov_b64 s[40:41], -1
	s_and_b64 vcc, exec, s[38:39]
	s_cbranch_vccz .LBB0_230
	s_add_i32 s12, s101, 0xfffffdc0
	s_mul_i32 s13, s12, 0xcccd
	s_lshr_b32 s36, s13, 20
	s_mul_i32 s13, s36, 0xffffffec
	s_add_i32 s13, s13, s12
	s_lshl_b32 s64, s13, 6
	s_mul_i32 s12, s36, 0x900
	s_add_i32 s29, s64, s12
	s_mov_b64 s[40:41], 0
.LBB0_230:
	s_andn2_b64 vcc, exec, s[40:41]
	s_cbranch_vccnz .LBB0_232
	s_mul_hi_i32 s12, s101, 0x38e38e39
	s_lshr_b32 s13, s12, 31
	s_ashr_i32 s12, s12, 3
	s_add_i32 s36, s12, s13
	s_lshl_b32 s29, s101, 6
	s_mul_i32 s12, s36, 0xfffff700
	s_add_i32 s64, s12, s29
